# P4 boundary-tile conv: one wait for the n=1 weights ahead of the row groups, the per-group vmcnt ladders (which only waited for the previous group's stores) removed
# baseline (speedup 1.0000x reference)
; __device__ __forceinline__ u32x2 pack4(f32x4 a) { u32x2 w; w.x = cvt_pk_bf16(a[0], a[1]); w.y = cvt_pk_bf16(a[2], a[3]); return w; }
; __device__ __forceinline__ float dpp_ror1(float v) { return __builtin_bit_cast(float, __builtin_amdgcn_update_dpp(0, __builtin_bit_cast(int, v), 0x121, 0xf, 0xf, false)); }
; __device__ __forceinline__ float dpp_ror15(float v) { return __builtin_bit_cast(float, __builtin_amdgcn_update_dpp(0, __builtin_bit_cast(int, v), 0x12F, 0xf, 0xf, false)); }
;     template <bool BND> __device__ __forceinline__ void conv_gate(f32x4 (&acc)[2][2][4][2], const Unit& u, int wr, int wc, int fr, int fq, int tok0, int pcol) const {
;     ...
;                 for (int m = 0; m < 4; ++m) {
;                     const int r = ai * 128 + wr * 64 + m * 16 + fr, tok = tok0 + r;
;                     bool isfirst = false, islast = false;
;                     if (BND) { const int S1 = (tok < NPROMPT ? SEQP : SEQS) - 1, pos = tok & S1; isfirst = pos == 0; islast = pos == S1; }
;                     f32x4 cv[2];
; #pragma unroll
;                     for (int bj = 0; bj < 2; ++bj) {
;                         const f32x4 cur = acc[ai][bj][m][n];
;                         const f32x4 ups = m > 0 ? acc[ai][bj][m > 0 ? m - 1 : 0][n] : pe[bj];
;                         const f32x4 dns = m < 3 ? acc[ai][bj][m < 3 ? m + 1 : 3][n] : ne[bj];
;                         f32x4 prev, next;
; #pragma unroll
;                         for (int j = 0; j < 4; ++j) {
;                             const float t1 = fr == 15 ? ups[j] : cur[j]; float pv = dpp_ror1(t1);
;                             const float t2 = fr == 0 ? dns[j] : cur[j]; float nx = dpp_ror15(t2);
;                             if (BND) { prev[j] = isfirst ? 0.f : pv; next[j] = islast ? 0.f : nx; } else { prev[j] = pv; next[j] = nx; }
;                         }
;                         cv[bj] = w0[bj] * prev + w1[bj] * cur + w2[bj] * next + bb[bj];
;                     }
;                     f32x4 a;
; #pragma unroll
;                     for (int j = 0; j < 4; ++j) { const float g = cv[0][j]; const float sg = __builtin_amdgcn_rcpf(1.0f + __builtin_amdgcn_exp2f(-1.4426950408889634f * g)); a[j] = g * sg * cv[1][j]; }
;                     if (r >= 1 && r <= 254 && (!BND || tok < MTOK)) *(u32x2*)(act + (size_t)tok * DFF + fcol + 4 * n) = pack4(a);
;                     asm volatile("" ::: "memory");
.LBB0_736:
	s_waitcnt lgkmcnt(0)
	v_cndmask_b32_e64 v72, v0, v72, s[8:9]
	v_cndmask_b32_e64 v81, v0, v160, s[6:7]
	v_cndmask_b32_e64 v73, v1, v73, s[8:9]
	v_mov_b32_dpp v80, v72 row_ror:1 row_mask:0xf bank_mask:0xf
	v_cndmask_b32_e64 v82, v1, v161, s[6:7]
	v_cndmask_b32_e64 v74, v2, v74, s[8:9]
	v_mov_b32_dpp v72, v81 row_ror:15 row_mask:0xf bank_mask:0xf
	v_cndmask_b32_e64 v83, v2, v158, s[6:7]
	v_cndmask_b32_e64 v75, v3, v75, s[8:9]
	v_mov_b32_dpp v81, v73 row_ror:1 row_mask:0xf bank_mask:0xf
	v_cndmask_b32_e64 v84, v3, v159, s[6:7]
	v_cndmask_b32_e64 v85, v4, v164, s[6:7]
	v_mov_b32_dpp v73, v82 row_ror:15 row_mask:0xf bank_mask:0xf
	v_cndmask_b32_e64 v86, v5, v165, s[6:7]
	v_cndmask_b32_e64 v87, v6, v162, s[6:7]
	v_mov_b32_dpp v82, v74 row_ror:1 row_mask:0xf bank_mask:0xf
	v_cndmask_b32_e64 v88, v7, v163, s[6:7]
	s_nop 0
	v_mov_b32_dpp v74, v83 row_ror:15 row_mask:0xf bank_mask:0xf
	v_mov_b32_dpp v83, v75 row_ror:1 row_mask:0xf bank_mask:0xf
	v_mov_b32_dpp v75, v84 row_ror:15 row_mask:0xf bank_mask:0xf
	v_cndmask_b32_e64 v84, v4, v76, s[8:9]
	s_nop 1
	v_mov_b32_dpp v76, v84 row_ror:1 row_mask:0xf bank_mask:0xf
	v_mov_b32_dpp v84, v85 row_ror:15 row_mask:0xf bank_mask:0xf
	v_cndmask_b32_e64 v85, v5, v77, s[8:9]
	s_nop 1
	v_mov_b32_dpp v77, v85 row_ror:1 row_mask:0xf bank_mask:0xf
	v_mov_b32_dpp v85, v86 row_ror:15 row_mask:0xf bank_mask:0xf
	v_cndmask_b32_e64 v86, v6, v78, s[8:9]
	s_nop 1
	v_mov_b32_dpp v78, v86 row_ror:1 row_mask:0xf bank_mask:0xf
	v_mov_b32_dpp v86, v87 row_ror:15 row_mask:0xf bank_mask:0xf
	v_cndmask_b32_e64 v87, v7, v79, s[8:9]
	s_nop 1
	v_mov_b32_dpp v79, v87 row_ror:1 row_mask:0xf bank_mask:0xf
	v_mov_b32_dpp v87, v88 row_ror:15 row_mask:0xf bank_mask:0xf
	s_waitcnt vmcnt(0)
	s_and_saveexec_b64 s[10:11], s[0:1]
	s_mov_b32 s38, s93
	s_cbranch_execz .LBB0_738
	v_cndmask_b32_e64 v82, v82, 0, s[20:21]
	v_cndmask_b32_e64 v83, v83, 0, s[20:21]
	v_pk_mul_f32 v[82:83], v[42:43], v[82:83]
	v_cndmask_b32_e64 v74, v74, 0, s[12:13]
	v_pk_fma_f32 v[82:83], v[2:3], v[46:47], v[82:83]
	v_cndmask_b32_e64 v75, v75, 0, s[12:13]
	v_pk_fma_f32 v[74:75], v[38:39], v[74:75], v[82:83]
	v_cndmask_b32_e64 v80, v80, 0, s[20:21]
	v_pk_add_f32 v[74:75], v[34:35], v[74:75]
	v_cndmask_b32_e64 v81, v81, 0, s[20:21]
	v_mul_f32_e32 v82, 0xbfb8aa3b, v75
	v_exp_f32_e32 v82, v82
	v_pk_mul_f32 v[80:81], v[40:41], v[80:81]
	v_cndmask_b32_e64 v72, v72, 0, s[12:13]
	v_pk_fma_f32 v[80:81], v[0:1], v[44:45], v[80:81]
	v_cndmask_b32_e64 v73, v73, 0, s[12:13]
	v_pk_fma_f32 v[72:73], v[36:37], v[72:73], v[80:81]
	v_add_f32_e32 v80, 1.0, v82
	v_cndmask_b32_e64 v78, v78, 0, s[20:21]
	v_cndmask_b32_e64 v79, v79, 0, s[20:21]
	v_rcp_f32_e32 v80, v80
	v_mul_f32_e32 v81, 0xbfb8aa3b, v74
	v_pk_mul_f32 v[78:79], v[62:63], v[78:79]
	v_exp_f32_e32 v81, v81
	v_cndmask_b32_e64 v86, v86, 0, s[12:13]
	v_cndmask_b32_e64 v87, v87, 0, s[12:13]
	v_pk_fma_f32 v[78:79], v[6:7], v[58:59], v[78:79]
	v_pk_add_f32 v[72:73], v[32:33], v[72:73]
	v_pk_fma_f32 v[78:79], v[54:55], v[86:87], v[78:79]
	v_mul_f32_e32 v75, v75, v80
	v_pk_add_f32 v[78:79], v[50:51], v[78:79]
	v_mul_f32_e32 v80, 0xbfb8aa3b, v73
	v_mul_f32_e32 v75, v75, v79
	v_add_f32_e32 v79, 1.0, v81
	v_mul_f32_e32 v81, 0xbfb8aa3b, v72
	v_rcp_f32_e32 v79, v79
	v_exp_f32_e32 v80, v80
	v_exp_f32_e32 v81, v81
	v_cndmask_b32_e64 v76, v76, 0, s[20:21]
	v_mul_f32_e32 v74, v74, v79
	v_add_f32_e32 v79, 1.0, v80
	v_add_f32_e32 v80, 1.0, v81
	v_cndmask_b32_e64 v77, v77, 0, s[20:21]
	v_rcp_f32_e32 v79, v79
	v_rcp_f32_e32 v80, v80
	v_pk_mul_f32 v[76:77], v[60:61], v[76:77]
	v_cndmask_b32_e64 v84, v84, 0, s[12:13]
	v_cndmask_b32_e64 v85, v85, 0, s[12:13]
	v_pk_fma_f32 v[76:77], v[4:5], v[56:57], v[76:77]
	v_mul_f32_e32 v73, v73, v79
	v_pk_fma_f32 v[76:77], v[52:53], v[84:85], v[76:77]
	v_mul_f32_e32 v72, v72, v80
	v_pk_add_f32 v[76:77], v[48:49], v[76:77]
	v_mul_f32_e32 v74, v74, v78
	v_mul_f32_e32 v73, v73, v77
	v_mul_f32_e32 v72, v72, v76
	v_cvt_pk_bf16_f32 v72, v72, v73
	v_cvt_pk_bf16_f32 v73, v74, v75
	v_mov_b64_e32 v[74:75], s[88:89]
	s_movk_i32 s0, 0x1600
	v_mad_i64_i32 v[74:75], s[0:1], v152, s0, v[74:75]
	v_lshl_add_u64 v[74:75], v[190:191], 1, v[74:75]
	global_store_dwordx2 v[74:75], v[72:73], off offset:8
.LBB0_738:
	s_or_b64 exec, exec, s[10:11]
	v_cndmask_b32_e64 v0, v160, v0, s[8:9]
	v_cndmask_b32_e64 v73, v160, v168, s[6:7]
	v_cndmask_b32_e64 v1, v161, v1, s[8:9]
	v_mov_b32_dpp v72, v0 row_ror:1 row_mask:0xf bank_mask:0xf
	v_cndmask_b32_e64 v74, v161, v169, s[6:7]
	v_cndmask_b32_e64 v2, v158, v2, s[8:9]
	v_mov_b32_dpp v0, v73 row_ror:15 row_mask:0xf bank_mask:0xf
	v_cndmask_b32_e64 v75, v158, v166, s[6:7]
	v_cndmask_b32_e64 v3, v159, v3, s[8:9]
	v_mov_b32_dpp v73, v1 row_ror:1 row_mask:0xf bank_mask:0xf
	v_cndmask_b32_e64 v76, v159, v167, s[6:7]
	v_cndmask_b32_e64 v77, v164, v172, s[6:7]
	v_mov_b32_dpp v1, v74 row_ror:15 row_mask:0xf bank_mask:0xf
	v_cndmask_b32_e64 v78, v165, v173, s[6:7]
	v_cndmask_b32_e64 v79, v162, v170, s[6:7]
	v_mov_b32_dpp v74, v2 row_ror:1 row_mask:0xf bank_mask:0xf
	v_cndmask_b32_e64 v80, v163, v171, s[6:7]
	s_nop 0
	v_mov_b32_dpp v2, v75 row_ror:15 row_mask:0xf bank_mask:0xf
	v_mov_b32_dpp v75, v3 row_ror:1 row_mask:0xf bank_mask:0xf
	v_mov_b32_dpp v3, v76 row_ror:15 row_mask:0xf bank_mask:0xf
	v_cndmask_b32_e64 v76, v164, v4, s[8:9]
	s_nop 1
	v_mov_b32_dpp v4, v76 row_ror:1 row_mask:0xf bank_mask:0xf
	v_mov_b32_dpp v76, v77 row_ror:15 row_mask:0xf bank_mask:0xf
	v_cndmask_b32_e64 v77, v165, v5, s[8:9]
	s_nop 1
	v_mov_b32_dpp v5, v77 row_ror:1 row_mask:0xf bank_mask:0xf
	v_mov_b32_dpp v77, v78 row_ror:15 row_mask:0xf bank_mask:0xf
	v_cndmask_b32_e64 v78, v162, v6, s[8:9]
	s_nop 1
	v_mov_b32_dpp v6, v78 row_ror:1 row_mask:0xf bank_mask:0xf
	v_mov_b32_dpp v78, v79 row_ror:15 row_mask:0xf bank_mask:0xf
	v_cndmask_b32_e64 v79, v163, v7, s[8:9]
	s_nop 1
	v_mov_b32_dpp v7, v79 row_ror:1 row_mask:0xf bank_mask:0xf
	v_mov_b32_dpp v79, v80 row_ror:15 row_mask:0xf bank_mask:0xf
	s_and_saveexec_b64 s[0:1], s[52:53]
	v_readlane_b32 s62, v255, 36
	v_readlane_b32 s93, v255, 38
	v_readlane_b32 s63, v255, 37
	s_cbranch_execz .LBB0_740
; __device__ __forceinline__ u32x2 pack4(f32x4 a) { u32x2 w; w.x = cvt_pk_bf16(a[0], a[1]); w.y = cvt_pk_bf16(a[2], a[3]); return w; }
; __device__ __forceinline__ float dpp_ror1(float v) { return __builtin_bit_cast(float, __builtin_amdgcn_update_dpp(0, __builtin_bit_cast(int, v), 0x121, 0xf, 0xf, false)); }
; __device__ __forceinline__ float dpp_ror15(float v) { return __builtin_bit_cast(float, __builtin_amdgcn_update_dpp(0, __builtin_bit_cast(int, v), 0x12F, 0xf, 0xf, false)); }
;     template <bool BND> __device__ __forceinline__ void conv_gate(f32x4 (&acc)[2][2][4][2], const Unit& u, int wr, int wc, int fr, int fq, int tok0, int pcol) const {
;     ...
;                 for (int m = 0; m < 4; ++m) {
;                     const int r = ai * 128 + wr * 64 + m * 16 + fr, tok = tok0 + r;
;                     bool isfirst = false, islast = false;
;                     if (BND) { const int S1 = (tok < NPROMPT ? SEQP : SEQS) - 1, pos = tok & S1; isfirst = pos == 0; islast = pos == S1; }
;                     f32x4 cv[2];
; #pragma unroll
;                     for (int bj = 0; bj < 2; ++bj) {
;                         const f32x4 cur = acc[ai][bj][m][n];
;                         const f32x4 ups = m > 0 ? acc[ai][bj][m > 0 ? m - 1 : 0][n] : pe[bj];
;                         const f32x4 dns = m < 3 ? acc[ai][bj][m < 3 ? m + 1 : 3][n] : ne[bj];
;                         f32x4 prev, next;
; #pragma unroll
;                         for (int j = 0; j < 4; ++j) {
;                             const float t1 = fr == 15 ? ups[j] : cur[j]; float pv = dpp_ror1(t1);
;                             const float t2 = fr == 0 ? dns[j] : cur[j]; float nx = dpp_ror15(t2);
;                             if (BND) { prev[j] = isfirst ? 0.f : pv; next[j] = islast ? 0.f : nx; } else { prev[j] = pv; next[j] = nx; }
;                         }
;                         cv[bj] = w0[bj] * prev + w1[bj] * cur + w2[bj] * next + bb[bj];
;                     }
;                     f32x4 a;
; #pragma unroll
;                     for (int j = 0; j < 4; ++j) { const float g = cv[0][j]; const float sg = __builtin_amdgcn_rcpf(1.0f + __builtin_amdgcn_exp2f(-1.4426950408889634f * g)); a[j] = g * sg * cv[1][j]; }
;                     if (r >= 1 && r <= 254 && (!BND || tok < MTOK)) *(u32x2*)(act + (size_t)tok * DFF + fcol + 4 * n) = pack4(a);
;                     asm volatile("" ::: "memory");
	v_cndmask_b32_e64 v74, v74, 0, s[22:23]
	v_cndmask_b32_e64 v75, v75, 0, s[22:23]
	v_pk_mul_f32 v[74:75], v[42:43], v[74:75]
	v_cndmask_b32_e64 v2, v2, 0, s[14:15]
	v_pk_fma_f32 v[74:75], v[158:159], v[46:47], v[74:75]
	v_cndmask_b32_e64 v3, v3, 0, s[14:15]
	v_pk_fma_f32 v[2:3], v[38:39], v[2:3], v[74:75]
	v_cndmask_b32_e64 v72, v72, 0, s[22:23]
	v_pk_add_f32 v[2:3], v[34:35], v[2:3]
	v_cndmask_b32_e64 v73, v73, 0, s[22:23]
	v_mul_f32_e32 v74, 0xbfb8aa3b, v3
	v_exp_f32_e32 v74, v74
	v_pk_mul_f32 v[72:73], v[40:41], v[72:73]
	v_cndmask_b32_e64 v0, v0, 0, s[14:15]
	v_pk_fma_f32 v[72:73], v[160:161], v[44:45], v[72:73]
	v_cndmask_b32_e64 v1, v1, 0, s[14:15]
	v_pk_fma_f32 v[0:1], v[36:37], v[0:1], v[72:73]
	v_add_f32_e32 v72, 1.0, v74
	v_cndmask_b32_e64 v6, v6, 0, s[22:23]
	v_cndmask_b32_e64 v7, v7, 0, s[22:23]
	v_rcp_f32_e32 v72, v72
	v_mul_f32_e32 v73, 0xbfb8aa3b, v2
	v_pk_mul_f32 v[6:7], v[62:63], v[6:7]
	v_exp_f32_e32 v73, v73
	v_cndmask_b32_e64 v78, v78, 0, s[14:15]
	v_cndmask_b32_e64 v79, v79, 0, s[14:15]
	v_pk_fma_f32 v[6:7], v[162:163], v[58:59], v[6:7]
	v_pk_add_f32 v[0:1], v[32:33], v[0:1]
	v_pk_fma_f32 v[6:7], v[54:55], v[78:79], v[6:7]
	v_mul_f32_e32 v3, v3, v72
	v_pk_add_f32 v[6:7], v[50:51], v[6:7]
	v_mul_f32_e32 v72, 0xbfb8aa3b, v1
	v_mul_f32_e32 v3, v3, v7
	v_add_f32_e32 v7, 1.0, v73
	v_mul_f32_e32 v73, 0xbfb8aa3b, v0
	v_rcp_f32_e32 v7, v7
	v_exp_f32_e32 v72, v72
	v_exp_f32_e32 v73, v73
	v_cndmask_b32_e64 v4, v4, 0, s[22:23]
	v_mul_f32_e32 v2, v2, v7
	v_add_f32_e32 v7, 1.0, v72
	v_add_f32_e32 v72, 1.0, v73
	v_cndmask_b32_e64 v5, v5, 0, s[22:23]
	v_rcp_f32_e32 v7, v7
	v_rcp_f32_e32 v72, v72
	v_pk_mul_f32 v[4:5], v[60:61], v[4:5]
	v_cndmask_b32_e64 v76, v76, 0, s[14:15]
	v_cndmask_b32_e64 v77, v77, 0, s[14:15]
	v_pk_fma_f32 v[4:5], v[164:165], v[56:57], v[4:5]
	v_mul_f32_e32 v1, v1, v7
	v_pk_fma_f32 v[4:5], v[52:53], v[76:77], v[4:5]
	v_mul_f32_e32 v0, v0, v72
	v_pk_add_f32 v[4:5], v[48:49], v[4:5]
	v_mul_f32_e32 v2, v2, v6
	v_mul_f32_e32 v1, v1, v5
	v_mul_f32_e32 v0, v0, v4
	v_cvt_pk_bf16_f32 v0, v0, v1
	v_cvt_pk_bf16_f32 v1, v2, v3
	v_mov_b64_e32 v[2:3], s[88:89]
	s_movk_i32 s4, 0x1600
	v_mad_i64_i32 v[2:3], s[4:5], v104, s4, v[2:3]
	v_lshl_add_u64 v[2:3], v[190:191], 1, v[2:3]
	global_store_dwordx2 v[2:3], v[0:1], off offset:8
.LBB0_740:
	s_or_b64 exec, exec, s[0:1]
	v_cndmask_b32_e64 v0, v168, v160, s[8:9]
	v_cndmask_b32_e64 v1, v168, v16, s[6:7]
	s_nop 0
	v_mov_b32_dpp v3, v0 row_ror:1 row_mask:0xf bank_mask:0xf
	v_cndmask_b32_e64 v2, v169, v17, s[6:7]
	v_mov_b32_dpp v0, v1 row_ror:15 row_mask:0xf bank_mask:0xf
	v_cndmask_b32_e64 v1, v169, v161, s[8:9]
	v_cndmask_b32_e64 v4, v166, v18, s[6:7]
	s_nop 0
	v_mov_b32_dpp v5, v1 row_ror:1 row_mask:0xf bank_mask:0xf
	v_cndmask_b32_e64 v72, v167, v19, s[6:7]
	v_cndmask_b32_e64 v73, v172, v164, s[8:9]
	v_mov_b32_dpp v1, v2 row_ror:15 row_mask:0xf bank_mask:0xf
	v_cndmask_b32_e64 v2, v166, v158, s[8:9]
	v_cndmask_b32_e64 v75, v173, v165, s[8:9]
	s_nop 0
	v_mov_b32_dpp v6, v2 row_ror:1 row_mask:0xf bank_mask:0xf
	v_cndmask_b32_e64 v77, v170, v162, s[8:9]
	v_mov_b32_dpp v2, v4 row_ror:15 row_mask:0xf bank_mask:0xf
	v_cndmask_b32_e64 v4, v167, v159, s[8:9]
	v_cndmask_b32_e64 v79, v171, v163, s[8:9]
	s_nop 0
	v_mov_b32_dpp v7, v4 row_ror:1 row_mask:0xf bank_mask:0xf
	v_cndmask_b32_e64 v80, v171, v23, s[6:7]
	s_nop 0
	v_mov_b32_dpp v4, v72 row_ror:15 row_mask:0xf bank_mask:0xf
	v_mov_b32_dpp v72, v73 row_ror:1 row_mask:0xf bank_mask:0xf
	v_cndmask_b32_e64 v73, v172, v20, s[6:7]
	s_nop 1
	v_mov_b32_dpp v74, v73 row_ror:15 row_mask:0xf bank_mask:0xf
	v_mov_b32_dpp v73, v75 row_ror:1 row_mask:0xf bank_mask:0xf
	v_cndmask_b32_e64 v75, v173, v21, s[6:7]
	s_nop 1
	v_mov_b32_dpp v76, v75 row_ror:15 row_mask:0xf bank_mask:0xf
	v_mov_b32_dpp v75, v77 row_ror:1 row_mask:0xf bank_mask:0xf
	v_cndmask_b32_e64 v77, v170, v22, s[6:7]
	s_nop 1
	v_mov_b32_dpp v78, v77 row_ror:15 row_mask:0xf bank_mask:0xf
	v_mov_b32_dpp v77, v79 row_ror:1 row_mask:0xf bank_mask:0xf
	v_mov_b32_dpp v79, v80 row_ror:15 row_mask:0xf bank_mask:0xf
	s_and_saveexec_b64 s[0:1], s[84:85]
	s_cbranch_execz .LBB0_742
	v_cndmask_b32_e64 v6, v6, 0, s[26:27]
	v_cndmask_b32_e64 v7, v7, 0, s[26:27]
	v_pk_mul_f32 v[6:7], v[42:43], v[6:7]
	v_cndmask_b32_e64 v81, v76, 0, s[16:17]
	v_cndmask_b32_e64 v76, v3, 0, s[26:27]
	v_pk_fma_f32 v[6:7], v[166:167], v[46:47], v[6:7]
	v_cndmask_b32_e64 v2, v2, 0, s[16:17]
	v_cndmask_b32_e64 v3, v4, 0, s[16:17]
	v_pk_fma_f32 v[2:3], v[38:39], v[2:3], v[6:7]
	v_cndmask_b32_e64 v80, v74, 0, s[16:17]
	v_pk_add_f32 v[2:3], v[34:35], v[2:3]
	v_cndmask_b32_e64 v74, v75, 0, s[26:27]
	v_mul_f32_e32 v4, 0xbfb8aa3b, v3
	v_exp_f32_e32 v4, v4
	v_cndmask_b32_e64 v75, v77, 0, s[26:27]
	v_cndmask_b32_e64 v77, v5, 0, s[26:27]
	v_mul_f32_e32 v5, 0xbfb8aa3b, v2
	v_add_f32_e32 v4, 1.0, v4
	v_pk_mul_f32 v[76:77], v[40:41], v[76:77]
	v_rcp_f32_e32 v4, v4
	v_exp_f32_e32 v5, v5
	v_pk_fma_f32 v[76:77], v[168:169], v[44:45], v[76:77]
	v_cndmask_b32_e64 v0, v0, 0, s[16:17]
	v_cndmask_b32_e64 v1, v1, 0, s[16:17]
	v_pk_fma_f32 v[0:1], v[36:37], v[0:1], v[76:77]
	v_mul_f32_e32 v3, v3, v4
	v_pk_add_f32 v[0:1], v[32:33], v[0:1]
	v_add_f32_e32 v4, 1.0, v5
	v_mul_f32_e32 v5, 0xbfb8aa3b, v1
	v_mul_f32_e32 v6, 0xbfb8aa3b, v0
	v_rcp_f32_e32 v4, v4
	v_exp_f32_e32 v5, v5
	v_exp_f32_e32 v6, v6
	v_cndmask_b32_e64 v72, v72, 0, s[26:27]
	v_mul_f32_e32 v2, v2, v4
	v_add_f32_e32 v4, 1.0, v5
	v_add_f32_e32 v5, 1.0, v6
	v_cndmask_b32_e64 v73, v73, 0, s[26:27]
	v_rcp_f32_e32 v4, v4
	v_rcp_f32_e32 v5, v5
	v_pk_mul_f32 v[74:75], v[62:63], v[74:75]
	v_pk_mul_f32 v[72:73], v[60:61], v[72:73]
	v_cndmask_b32_e64 v78, v78, 0, s[16:17]
	v_cndmask_b32_e64 v79, v79, 0, s[16:17]
	v_pk_fma_f32 v[72:73], v[172:173], v[56:57], v[72:73]
	v_pk_fma_f32 v[74:75], v[170:171], v[58:59], v[74:75]
	v_pk_fma_f32 v[72:73], v[52:53], v[80:81], v[72:73]
	v_pk_fma_f32 v[74:75], v[54:55], v[78:79], v[74:75]
	v_pk_add_f32 v[72:73], v[48:49], v[72:73]
	v_pk_add_f32 v[74:75], v[50:51], v[74:75]
	v_mul_f32_e32 v1, v1, v4
	v_mul_f32_e32 v0, v0, v5
	v_mul_f32_e32 v3, v3, v75
	v_mul_f32_e32 v2, v2, v74
	v_mul_f32_e32 v1, v1, v73
	v_mul_f32_e32 v0, v0, v72
	v_cvt_pk_bf16_f32 v0, v0, v1
	v_cvt_pk_bf16_f32 v1, v2, v3
	v_mov_b64_e32 v[2:3], s[88:89]
	s_movk_i32 s4, 0x1600
	v_mad_i64_i32 v[2:3], s[4:5], v105, s4, v[2:3]
	v_lshl_add_u64 v[2:3], v[190:191], 1, v[2:3]
	global_store_dwordx2 v[2:3], v[0:1], off offset:8
; __device__ __forceinline__ u32x2 pack4(f32x4 a) { u32x2 w; w.x = cvt_pk_bf16(a[0], a[1]); w.y = cvt_pk_bf16(a[2], a[3]); return w; }
; __device__ __forceinline__ float dpp_ror1(float v) { return __builtin_bit_cast(float, __builtin_amdgcn_update_dpp(0, __builtin_bit_cast(int, v), 0x121, 0xf, 0xf, false)); }
; __device__ __forceinline__ float dpp_ror15(float v) { return __builtin_bit_cast(float, __builtin_amdgcn_update_dpp(0, __builtin_bit_cast(int, v), 0x12F, 0xf, 0xf, false)); }
;     template <bool BND> __device__ __forceinline__ void conv_gate(f32x4 (&acc)[2][2][4][2], const Unit& u, int wr, int wc, int fr, int fq, int tok0, int pcol) const {
;     ...
;                 for (int m = 0; m < 4; ++m) {
;                     const int r = ai * 128 + wr * 64 + m * 16 + fr, tok = tok0 + r;
;                     bool isfirst = false, islast = false;
;                     if (BND) { const int S1 = (tok < NPROMPT ? SEQP : SEQS) - 1, pos = tok & S1; isfirst = pos == 0; islast = pos == S1; }
;                     f32x4 cv[2];
; #pragma unroll
;                     for (int bj = 0; bj < 2; ++bj) {
;                         const f32x4 cur = acc[ai][bj][m][n];
;                         const f32x4 ups = m > 0 ? acc[ai][bj][m > 0 ? m - 1 : 0][n] : pe[bj];
;                         const f32x4 dns = m < 3 ? acc[ai][bj][m < 3 ? m + 1 : 3][n] : ne[bj];
;                         f32x4 prev, next;
; #pragma unroll
;                         for (int j = 0; j < 4; ++j) {
;                             const float t1 = fr == 15 ? ups[j] : cur[j]; float pv = dpp_ror1(t1);
;                             const float t2 = fr == 0 ? dns[j] : cur[j]; float nx = dpp_ror15(t2);
;                             if (BND) { prev[j] = isfirst ? 0.f : pv; next[j] = islast ? 0.f : nx; } else { prev[j] = pv; next[j] = nx; }
;                         }
;                         cv[bj] = w0[bj] * prev + w1[bj] * cur + w2[bj] * next + bb[bj];
;                     }
;                     f32x4 a;
; #pragma unroll
;                     for (int j = 0; j < 4; ++j) { const float g = cv[0][j]; const float sg = __builtin_amdgcn_rcpf(1.0f + __builtin_amdgcn_exp2f(-1.4426950408889634f * g)); a[j] = g * sg * cv[1][j]; }
;                     if (r >= 1 && r <= 254 && (!BND || tok < MTOK)) *(u32x2*)(act + (size_t)tok * DFF + fcol + 4 * n) = pack4(a);
;                     asm volatile("" ::: "memory");
.LBB0_742:
	s_or_b64 exec, exec, s[0:1]
	v_cndmask_b32_e64 v0, v16, v168, s[8:9]
	v_cndmask_b32_e64 v1, v16, v64, s[6:7]
	s_nop 0
	v_mov_b32_dpp v3, v0 row_ror:1 row_mask:0xf bank_mask:0xf
	v_cndmask_b32_e64 v2, v17, v65, s[6:7]
	v_mov_b32_dpp v0, v1 row_ror:15 row_mask:0xf bank_mask:0xf
	v_cndmask_b32_e64 v1, v17, v169, s[8:9]
	v_cndmask_b32_e64 v4, v18, v66, s[6:7]
	s_nop 0
	v_mov_b32_dpp v5, v1 row_ror:1 row_mask:0xf bank_mask:0xf
	v_cndmask_b32_e64 v64, v19, v67, s[6:7]
	v_cndmask_b32_e64 v65, v20, v172, s[8:9]
	v_mov_b32_dpp v1, v2 row_ror:15 row_mask:0xf bank_mask:0xf
	v_cndmask_b32_e64 v2, v18, v166, s[8:9]
	v_cndmask_b32_e64 v67, v21, v173, s[8:9]
	s_nop 0
	v_mov_b32_dpp v6, v2 row_ror:1 row_mask:0xf bank_mask:0xf
	v_cndmask_b32_e64 v72, v23, v171, s[8:9]
	s_nop 0
	v_mov_b32_dpp v2, v4 row_ror:15 row_mask:0xf bank_mask:0xf
	v_cndmask_b32_e64 v4, v19, v167, s[8:9]
	s_nop 1
	v_mov_b32_dpp v7, v4 row_ror:1 row_mask:0xf bank_mask:0xf
	v_mov_b32_dpp v4, v64 row_ror:15 row_mask:0xf bank_mask:0xf
	v_mov_b32_dpp v64, v65 row_ror:1 row_mask:0xf bank_mask:0xf
	v_cndmask_b32_e64 v65, v20, v68, s[6:7]
	s_nop 0
	s_nop 0
	v_mov_b32_dpp v66, v65 row_ror:15 row_mask:0xf bank_mask:0xf
	v_mov_b32_dpp v65, v67 row_ror:1 row_mask:0xf bank_mask:0xf
	v_cndmask_b32_e64 v67, v21, v69, s[6:7]
	v_cndmask_b32_e64 v69, v22, v170, s[8:9]
	s_nop 0
	v_mov_b32_dpp v68, v67 row_ror:15 row_mask:0xf bank_mask:0xf
	v_mov_b32_dpp v67, v69 row_ror:1 row_mask:0xf bank_mask:0xf
	v_cndmask_b32_e64 v69, v22, v70, s[6:7]
	s_nop 1
	v_mov_b32_dpp v70, v69 row_ror:15 row_mask:0xf bank_mask:0xf
	v_mov_b32_dpp v69, v72 row_ror:1 row_mask:0xf bank_mask:0xf
	v_cndmask_b32_e64 v72, v23, v71, s[6:7]
	s_nop 1
	v_mov_b32_dpp v71, v72 row_ror:15 row_mask:0xf bank_mask:0xf
	s_and_saveexec_b64 s[0:1], s[90:91]
	s_cbranch_execz .LBB0_744
	v_cndmask_b32_e64 v64, v64, 0, s[30:31]
	v_cndmask_b32_e64 v65, v65, 0, s[30:31]
	v_cndmask_b32_e64 v6, v6, 0, s[30:31]
	v_cndmask_b32_e64 v7, v7, 0, s[30:31]
	v_pk_mul_f32 v[64:65], v[60:61], v[64:65]
	v_pk_mul_f32 v[6:7], v[42:43], v[6:7]
	v_pk_fma_f32 v[20:21], v[20:21], v[56:57], v[64:65]
	v_cndmask_b32_e64 v64, v3, 0, s[30:31]
	v_pk_fma_f32 v[6:7], v[18:19], v[46:47], v[6:7]
	v_cndmask_b32_e64 v2, v2, 0, s[18:19]
	v_cndmask_b32_e64 v3, v4, 0, s[18:19]
	v_pk_fma_f32 v[2:3], v[38:39], v[2:3], v[6:7]
	v_cndmask_b32_e64 v65, v5, 0, s[30:31]
	v_pk_add_f32 v[2:3], v[34:35], v[2:3]
	v_pk_mul_f32 v[64:65], v[40:41], v[64:65]
	v_mul_f32_e32 v4, 0xbfb8aa3b, v3
	v_exp_f32_e32 v4, v4
	v_mul_f32_e32 v5, 0xbfb8aa3b, v2
	v_exp_f32_e32 v5, v5
	v_pk_fma_f32 v[16:17], v[16:17], v[44:45], v[64:65]
	v_add_f32_e32 v4, 1.0, v4
	v_rcp_f32_e32 v4, v4
	v_cndmask_b32_e64 v0, v0, 0, s[18:19]
	v_cndmask_b32_e64 v1, v1, 0, s[18:19]
	v_pk_fma_f32 v[0:1], v[36:37], v[0:1], v[16:17]
	v_mul_f32_e32 v3, v3, v4
	v_pk_add_f32 v[0:1], v[32:33], v[0:1]
	v_add_f32_e32 v4, 1.0, v5
	v_mul_f32_e32 v5, 0xbfb8aa3b, v1
	v_mul_f32_e32 v6, 0xbfb8aa3b, v0
	v_rcp_f32_e32 v4, v4
	v_exp_f32_e32 v5, v5
	v_exp_f32_e32 v6, v6
	v_cndmask_b32_e64 v72, v66, 0, s[18:19]
	v_mul_f32_e32 v2, v2, v4
	v_add_f32_e32 v4, 1.0, v5
	v_add_f32_e32 v5, 1.0, v6
	v_cndmask_b32_e64 v66, v67, 0, s[30:31]
	v_cndmask_b32_e64 v67, v69, 0, s[30:31]
	v_rcp_f32_e32 v4, v4
	v_rcp_f32_e32 v5, v5
	v_pk_mul_f32 v[66:67], v[62:63], v[66:67]
	v_cndmask_b32_e64 v73, v68, 0, s[18:19]
	v_cndmask_b32_e64 v70, v70, 0, s[18:19]
	v_cndmask_b32_e64 v71, v71, 0, s[18:19]
	v_pk_fma_f32 v[22:23], v[22:23], v[58:59], v[66:67]
	v_pk_fma_f32 v[20:21], v[52:53], v[72:73], v[20:21]
	v_pk_fma_f32 v[22:23], v[54:55], v[70:71], v[22:23]
	v_pk_add_f32 v[20:21], v[48:49], v[20:21]
	v_pk_add_f32 v[22:23], v[50:51], v[22:23]
	v_mul_f32_e32 v1, v1, v4
	v_mul_f32_e32 v0, v0, v5
	v_mul_f32_e32 v3, v3, v23
	v_mul_f32_e32 v2, v2, v22
	v_mul_f32_e32 v1, v1, v21
	v_mul_f32_e32 v0, v0, v20
	v_cvt_pk_bf16_f32 v0, v0, v1
	v_cvt_pk_bf16_f32 v1, v2, v3
	v_mov_b64_e32 v[2:3], s[88:89]
	s_movk_i32 s4, 0x1600
	v_mad_i64_i32 v[2:3], s[4:5], v106, s4, v[2:3]
	v_lshl_add_u64 v[2:3], v[190:191], 1, v[2:3]
	global_store_dwordx2 v[2:3], v[0:1], off offset:8

; #define LAS __attribute__((address_space(3)))
;     template <bool BND> __device__ __forceinline__ void conv_gate(f32x4 (&acc)[2][2][4][2], const Unit& u, int wr, int wc, int fr, int fq, int tok0, int pcol) const {
;     ...
;                     pe[bj] = blk > 0 ? *(const LAS f32x4*)(edge + ((blk - 1) * 2 + 1) * 256 + 128 * bj + pcol + 4 * n) : (f32x4){0.f, 0.f, 0.f, 0.f};
;                     ne[bj] = blk < 3 ? *(const LAS f32x4*)(edge + ((blk + 1) * 2 + 0) * 256 + 128 * bj + pcol + 4 * n) : (f32x4){0.f, 0.f, 0.f, 0.f};
;                 }
; #pragma unroll
;                 for (int m = 0; m < 4; ++m) {
;                     const int r = ai * 128 + wr * 64 + m * 16 + fr, tok = tok0 + r;
;                     bool isfirst = false, islast = false;
;                     if (BND) { const int S1 = (tok < NPROMPT ? SEQP : SEQS) - 1, pos = tok & S1; isfirst = pos == 0; islast = pos == S1; }
;                     f32x4 cv[2];
; #pragma unroll
;                     for (int bj = 0; bj < 2; ++bj) {
;                         const f32x4 cur = acc[ai][bj][m][n];
;                         const f32x4 ups = m > 0 ? acc[ai][bj][m > 0 ? m - 1 : 0][n] : pe[bj];
;                         const f32x4 dns = m < 3 ? acc[ai][bj][m < 3 ? m + 1 : 3][n] : ne[bj];
;                         f32x4 prev, next;
; #pragma unroll
;                         for (int j = 0; j < 4; ++j) {
;                             const float t1 = fr == 15 ? ups[j] : cur[j]; float pv = dpp_ror1(t1);
;                             const float t2 = fr == 0 ? dns[j] : cur[j]; float nx = dpp_ror15(t2);
;                             if (BND) { prev[j] = isfirst ? 0.f : pv; next[j] = islast ? 0.f : nx; } else { prev[j] = pv; next[j] = nx; }
;                         }
;                         cv[bj] = w0[bj] * prev + w1[bj] * cur + w2[bj] * next + bb[bj];
;                     }
;                     f32x4 a;
; #pragma unroll
;                     for (int j = 0; j < 4; ++j) { const float g = cv[0][j]; const float sg = __builtin_amdgcn_rcpf(1.0f + __builtin_amdgcn_exp2f(-1.4426950408889634f * g)); a[j] = g * sg * cv[1][j]; }
;                     if (r >= 1 && r <= 254 && (!BND || tok < MTOK)) *(u32x2*)(act + (size_t)tok * DFF + fcol + 4 * n) = pack4(a);
;                     asm volatile("" ::: "memory");
.LBB0_752:
	s_waitcnt lgkmcnt(0)
	v_cndmask_b32_e64 v16, v8, v16, s[8:9]
	v_cndmask_b32_e64 v65, v8, v176, s[6:7]
	v_cndmask_b32_e64 v17, v9, v17, s[8:9]
	v_mov_b32_dpp v64, v16 row_ror:1 row_mask:0xf bank_mask:0xf
	v_cndmask_b32_e64 v66, v9, v177, s[6:7]
	v_cndmask_b32_e64 v18, v10, v18, s[8:9]
	v_mov_b32_dpp v16, v65 row_ror:15 row_mask:0xf bank_mask:0xf
	v_cndmask_b32_e64 v67, v10, v174, s[6:7]
	v_cndmask_b32_e64 v19, v11, v19, s[8:9]
	v_mov_b32_dpp v65, v17 row_ror:1 row_mask:0xf bank_mask:0xf
	v_cndmask_b32_e64 v68, v11, v175, s[6:7]
	v_cndmask_b32_e64 v69, v12, v180, s[6:7]
	v_mov_b32_dpp v17, v66 row_ror:15 row_mask:0xf bank_mask:0xf
	v_cndmask_b32_e64 v70, v13, v181, s[6:7]
	v_cndmask_b32_e64 v71, v14, v178, s[6:7]
	v_mov_b32_dpp v66, v18 row_ror:1 row_mask:0xf bank_mask:0xf
	v_cndmask_b32_e64 v72, v15, v179, s[6:7]
	s_nop 0
	v_mov_b32_dpp v18, v67 row_ror:15 row_mask:0xf bank_mask:0xf
	v_mov_b32_dpp v67, v19 row_ror:1 row_mask:0xf bank_mask:0xf
	v_mov_b32_dpp v19, v68 row_ror:15 row_mask:0xf bank_mask:0xf
	v_cndmask_b32_e64 v68, v12, v20, s[8:9]
	s_nop 1
	v_mov_b32_dpp v20, v68 row_ror:1 row_mask:0xf bank_mask:0xf
	v_mov_b32_dpp v68, v69 row_ror:15 row_mask:0xf bank_mask:0xf
	v_cndmask_b32_e64 v69, v13, v21, s[8:9]
	s_nop 1
	v_mov_b32_dpp v21, v69 row_ror:1 row_mask:0xf bank_mask:0xf
	v_mov_b32_dpp v69, v70 row_ror:15 row_mask:0xf bank_mask:0xf
	v_cndmask_b32_e64 v70, v14, v22, s[8:9]
	s_nop 1
	v_mov_b32_dpp v22, v70 row_ror:1 row_mask:0xf bank_mask:0xf
	v_mov_b32_dpp v70, v71 row_ror:15 row_mask:0xf bank_mask:0xf
	v_cndmask_b32_e64 v71, v15, v23, s[8:9]
	s_nop 1
	v_mov_b32_dpp v23, v71 row_ror:1 row_mask:0xf bank_mask:0xf
	v_mov_b32_dpp v71, v72 row_ror:15 row_mask:0xf bank_mask:0xf
	s_and_saveexec_b64 s[0:1], s[66:67]
	s_mov_b32 s48, s79
	s_mov_b32 s50, s74
	s_movk_i32 s84, 0xfe
	s_cbranch_execz .LBB0_754
	v_cndmask_b32_e64 v66, v66, 0, s[40:41]
	v_cndmask_b32_e64 v67, v67, 0, s[40:41]
	v_pk_mul_f32 v[66:67], v[42:43], v[66:67]
	v_cndmask_b32_e64 v18, v18, 0, s[24:25]
	v_pk_fma_f32 v[66:67], v[10:11], v[46:47], v[66:67]
	v_cndmask_b32_e64 v19, v19, 0, s[24:25]
	v_pk_fma_f32 v[18:19], v[38:39], v[18:19], v[66:67]
	v_cndmask_b32_e64 v64, v64, 0, s[40:41]
	v_pk_add_f32 v[18:19], v[34:35], v[18:19]
	v_cndmask_b32_e64 v65, v65, 0, s[40:41]
	v_mul_f32_e32 v66, 0xbfb8aa3b, v19
	v_exp_f32_e32 v66, v66
	v_pk_mul_f32 v[64:65], v[40:41], v[64:65]
	v_cndmask_b32_e64 v16, v16, 0, s[24:25]
	v_pk_fma_f32 v[64:65], v[8:9], v[44:45], v[64:65]
	v_cndmask_b32_e64 v17, v17, 0, s[24:25]
	v_pk_fma_f32 v[16:17], v[36:37], v[16:17], v[64:65]
	v_add_f32_e32 v64, 1.0, v66
	v_cndmask_b32_e64 v22, v22, 0, s[40:41]
	v_cndmask_b32_e64 v23, v23, 0, s[40:41]
	v_rcp_f32_e32 v64, v64
	v_mul_f32_e32 v65, 0xbfb8aa3b, v18
	v_pk_mul_f32 v[22:23], v[62:63], v[22:23]
	v_exp_f32_e32 v65, v65
	v_cndmask_b32_e64 v70, v70, 0, s[24:25]
	v_cndmask_b32_e64 v71, v71, 0, s[24:25]
	v_pk_fma_f32 v[22:23], v[14:15], v[58:59], v[22:23]
	v_pk_add_f32 v[16:17], v[32:33], v[16:17]
	v_pk_fma_f32 v[22:23], v[54:55], v[70:71], v[22:23]
	v_mul_f32_e32 v19, v19, v64
	v_pk_add_f32 v[22:23], v[50:51], v[22:23]
	v_mul_f32_e32 v64, 0xbfb8aa3b, v17
	v_mul_f32_e32 v19, v19, v23
	v_add_f32_e32 v23, 1.0, v65
	v_mul_f32_e32 v65, 0xbfb8aa3b, v16
	v_rcp_f32_e32 v23, v23
	v_exp_f32_e32 v64, v64
	v_exp_f32_e32 v65, v65
	v_cndmask_b32_e64 v20, v20, 0, s[40:41]
	v_mul_f32_e32 v18, v18, v23
	v_add_f32_e32 v23, 1.0, v64
	v_add_f32_e32 v64, 1.0, v65
	v_cndmask_b32_e64 v21, v21, 0, s[40:41]
	v_rcp_f32_e32 v23, v23
	v_rcp_f32_e32 v64, v64
	v_pk_mul_f32 v[20:21], v[60:61], v[20:21]
	v_cndmask_b32_e64 v68, v68, 0, s[24:25]
	v_cndmask_b32_e64 v69, v69, 0, s[24:25]
	v_pk_fma_f32 v[20:21], v[12:13], v[56:57], v[20:21]
	v_mul_f32_e32 v17, v17, v23
	v_pk_fma_f32 v[20:21], v[52:53], v[68:69], v[20:21]
	v_mul_f32_e32 v16, v16, v64
	v_pk_add_f32 v[20:21], v[48:49], v[20:21]
	v_mul_f32_e32 v18, v18, v22
	v_mul_f32_e32 v17, v17, v21
	v_mul_f32_e32 v16, v16, v20
	v_cvt_pk_bf16_f32 v16, v16, v17
	v_cvt_pk_bf16_f32 v17, v18, v19
	v_mov_b64_e32 v[18:19], s[88:89]
	s_movk_i32 s4, 0x1600
	v_mad_i64_i32 v[18:19], s[4:5], v96, s4, v[18:19]
	v_lshl_add_u64 v[18:19], v[190:191], 1, v[18:19]
	global_store_dwordx2 v[18:19], v[16:17], off offset:8
; __device__ __forceinline__ u32x2 pack4(f32x4 a) { u32x2 w; w.x = cvt_pk_bf16(a[0], a[1]); w.y = cvt_pk_bf16(a[2], a[3]); return w; }
; __device__ __forceinline__ float dpp_ror1(float v) { return __builtin_bit_cast(float, __builtin_amdgcn_update_dpp(0, __builtin_bit_cast(int, v), 0x121, 0xf, 0xf, false)); }
; __device__ __forceinline__ float dpp_ror15(float v) { return __builtin_bit_cast(float, __builtin_amdgcn_update_dpp(0, __builtin_bit_cast(int, v), 0x12F, 0xf, 0xf, false)); }
;     template <bool BND> __device__ __forceinline__ void conv_gate(f32x4 (&acc)[2][2][4][2], const Unit& u, int wr, int wc, int fr, int fq, int tok0, int pcol) const {
;     ...
;                 for (int m = 0; m < 4; ++m) {
;                     const int r = ai * 128 + wr * 64 + m * 16 + fr, tok = tok0 + r;
;                     bool isfirst = false, islast = false;
;                     if (BND) { const int S1 = (tok < NPROMPT ? SEQP : SEQS) - 1, pos = tok & S1; isfirst = pos == 0; islast = pos == S1; }
;                     f32x4 cv[2];
; #pragma unroll
;                     for (int bj = 0; bj < 2; ++bj) {
;                         const f32x4 cur = acc[ai][bj][m][n];
;                         const f32x4 ups = m > 0 ? acc[ai][bj][m > 0 ? m - 1 : 0][n] : pe[bj];
;                         const f32x4 dns = m < 3 ? acc[ai][bj][m < 3 ? m + 1 : 3][n] : ne[bj];
;                         f32x4 prev, next;
; #pragma unroll
;                         for (int j = 0; j < 4; ++j) {
;                             const float t1 = fr == 15 ? ups[j] : cur[j]; float pv = dpp_ror1(t1);
;                             const float t2 = fr == 0 ? dns[j] : cur[j]; float nx = dpp_ror15(t2);
;                             if (BND) { prev[j] = isfirst ? 0.f : pv; next[j] = islast ? 0.f : nx; } else { prev[j] = pv; next[j] = nx; }
;                         }
;                         cv[bj] = w0[bj] * prev + w1[bj] * cur + w2[bj] * next + bb[bj];
;                     }
;                     f32x4 a;
; #pragma unroll
;                     for (int j = 0; j < 4; ++j) { const float g = cv[0][j]; const float sg = __builtin_amdgcn_rcpf(1.0f + __builtin_amdgcn_exp2f(-1.4426950408889634f * g)); a[j] = g * sg * cv[1][j]; }
;                     if (r >= 1 && r <= 254 && (!BND || tok < MTOK)) *(u32x2*)(act + (size_t)tok * DFF + fcol + 4 * n) = pack4(a);
;                     asm volatile("" ::: "memory");
.LBB0_754:
	s_or_b64 exec, exec, s[0:1]
	v_cndmask_b32_e64 v8, v176, v8, s[8:9]
	v_cndmask_b32_e64 v17, v176, v184, s[6:7]
	v_cndmask_b32_e64 v9, v177, v9, s[8:9]
	v_mov_b32_dpp v16, v8 row_ror:1 row_mask:0xf bank_mask:0xf
	v_cndmask_b32_e64 v18, v177, v185, s[6:7]
	v_cndmask_b32_e64 v10, v174, v10, s[8:9]
	v_mov_b32_dpp v8, v17 row_ror:15 row_mask:0xf bank_mask:0xf
	v_cndmask_b32_e64 v19, v174, v182, s[6:7]
	v_cndmask_b32_e64 v11, v175, v11, s[8:9]
	v_mov_b32_dpp v17, v9 row_ror:1 row_mask:0xf bank_mask:0xf
	v_cndmask_b32_e64 v20, v175, v183, s[6:7]
	v_cndmask_b32_e64 v21, v180, v188, s[6:7]
	v_mov_b32_dpp v9, v18 row_ror:15 row_mask:0xf bank_mask:0xf
	v_cndmask_b32_e64 v22, v181, v189, s[6:7]
	v_cndmask_b32_e64 v23, v178, v186, s[6:7]
	v_mov_b32_dpp v18, v10 row_ror:1 row_mask:0xf bank_mask:0xf
	v_cndmask_b32_e64 v64, v179, v187, s[6:7]
	s_nop 0
	v_mov_b32_dpp v10, v19 row_ror:15 row_mask:0xf bank_mask:0xf
	v_mov_b32_dpp v19, v11 row_ror:1 row_mask:0xf bank_mask:0xf
	v_mov_b32_dpp v11, v20 row_ror:15 row_mask:0xf bank_mask:0xf
	v_cndmask_b32_e64 v20, v180, v12, s[8:9]
	s_nop 1
	v_mov_b32_dpp v12, v20 row_ror:1 row_mask:0xf bank_mask:0xf
	v_mov_b32_dpp v20, v21 row_ror:15 row_mask:0xf bank_mask:0xf
	v_cndmask_b32_e64 v21, v181, v13, s[8:9]
	s_nop 1
	v_mov_b32_dpp v13, v21 row_ror:1 row_mask:0xf bank_mask:0xf
	v_mov_b32_dpp v21, v22 row_ror:15 row_mask:0xf bank_mask:0xf
	v_cndmask_b32_e64 v22, v178, v14, s[8:9]
	s_nop 1
	v_mov_b32_dpp v14, v22 row_ror:1 row_mask:0xf bank_mask:0xf
	v_mov_b32_dpp v22, v23 row_ror:15 row_mask:0xf bank_mask:0xf
	v_cndmask_b32_e64 v23, v179, v15, s[8:9]
	s_nop 1
	v_mov_b32_dpp v15, v23 row_ror:1 row_mask:0xf bank_mask:0xf
	v_mov_b32_dpp v23, v64 row_ror:15 row_mask:0xf bank_mask:0xf
	s_and_saveexec_b64 s[0:1], s[68:69]
	v_readlane_b32 s60, v255, 12
	v_readlane_b32 s61, v255, 13
	s_mov_b32 s56, 0x10000
	v_readlane_b32 s51, v255, 39
	v_readlane_b32 s57, v255, 40
	v_readlane_b32 s68, v255, 41
	s_mov_b32 s69, 0x20000
	v_readlane_b32 s74, v255, 42
	v_readlane_b32 s79, v255, 43
	s_cbranch_execz .LBB0_756
	v_cndmask_b32_e64 v18, v18, 0, s[42:43]
	v_cndmask_b32_e64 v19, v19, 0, s[42:43]
	v_pk_mul_f32 v[18:19], v[42:43], v[18:19]
	v_cndmask_b32_e64 v10, v10, 0, s[28:29]
	v_pk_fma_f32 v[18:19], v[174:175], v[46:47], v[18:19]
	v_cndmask_b32_e64 v11, v11, 0, s[28:29]
	v_pk_fma_f32 v[10:11], v[38:39], v[10:11], v[18:19]
	v_cndmask_b32_e64 v16, v16, 0, s[42:43]
	v_pk_add_f32 v[10:11], v[34:35], v[10:11]
	v_cndmask_b32_e64 v17, v17, 0, s[42:43]
	v_mul_f32_e32 v18, 0xbfb8aa3b, v11
	v_exp_f32_e32 v18, v18
	v_pk_mul_f32 v[16:17], v[40:41], v[16:17]
	v_cndmask_b32_e64 v8, v8, 0, s[28:29]
	v_pk_fma_f32 v[16:17], v[176:177], v[44:45], v[16:17]
	v_cndmask_b32_e64 v9, v9, 0, s[28:29]
	v_pk_fma_f32 v[8:9], v[36:37], v[8:9], v[16:17]
	v_add_f32_e32 v16, 1.0, v18
	v_cndmask_b32_e64 v14, v14, 0, s[42:43]
	v_cndmask_b32_e64 v15, v15, 0, s[42:43]
	v_rcp_f32_e32 v16, v16
	v_mul_f32_e32 v17, 0xbfb8aa3b, v10
	v_pk_mul_f32 v[14:15], v[62:63], v[14:15]
	v_exp_f32_e32 v17, v17
	v_cndmask_b32_e64 v22, v22, 0, s[28:29]
	v_cndmask_b32_e64 v23, v23, 0, s[28:29]
	v_pk_fma_f32 v[14:15], v[178:179], v[58:59], v[14:15]
	v_pk_add_f32 v[8:9], v[32:33], v[8:9]
	v_pk_fma_f32 v[14:15], v[54:55], v[22:23], v[14:15]
	v_mul_f32_e32 v11, v11, v16
	v_pk_add_f32 v[14:15], v[50:51], v[14:15]
	v_mul_f32_e32 v16, 0xbfb8aa3b, v9
	v_mul_f32_e32 v11, v11, v15
	v_add_f32_e32 v15, 1.0, v17
	v_mul_f32_e32 v17, 0xbfb8aa3b, v8
	v_rcp_f32_e32 v15, v15
	v_exp_f32_e32 v16, v16
	v_exp_f32_e32 v17, v17
	v_cndmask_b32_e64 v12, v12, 0, s[42:43]
	v_mul_f32_e32 v10, v10, v15
	v_add_f32_e32 v15, 1.0, v16
	v_add_f32_e32 v16, 1.0, v17
	v_cndmask_b32_e64 v13, v13, 0, s[42:43]
	v_rcp_f32_e32 v15, v15
	v_rcp_f32_e32 v16, v16
	v_pk_mul_f32 v[12:13], v[60:61], v[12:13]
	v_cndmask_b32_e64 v20, v20, 0, s[28:29]
	v_cndmask_b32_e64 v21, v21, 0, s[28:29]
	v_pk_fma_f32 v[12:13], v[180:181], v[56:57], v[12:13]
	v_mul_f32_e32 v9, v9, v15
	v_pk_fma_f32 v[12:13], v[52:53], v[20:21], v[12:13]
	v_mul_f32_e32 v8, v8, v16
	v_pk_add_f32 v[12:13], v[48:49], v[12:13]
	v_mul_f32_e32 v10, v10, v14
	v_mul_f32_e32 v9, v9, v13
	v_mul_f32_e32 v8, v8, v12
	v_cvt_pk_bf16_f32 v8, v8, v9
	v_cvt_pk_bf16_f32 v9, v10, v11
	v_mov_b64_e32 v[10:11], s[88:89]
	s_movk_i32 s4, 0x1600
	v_mad_i64_i32 v[10:11], s[4:5], v97, s4, v[10:11]
	v_lshl_add_u64 v[10:11], v[190:191], 1, v[10:11]
	global_store_dwordx2 v[10:11], v[8:9], off offset:8
; __device__ __forceinline__ u32x2 pack4(f32x4 a) { u32x2 w; w.x = cvt_pk_bf16(a[0], a[1]); w.y = cvt_pk_bf16(a[2], a[3]); return w; }
; __device__ __forceinline__ float dpp_ror1(float v) { return __builtin_bit_cast(float, __builtin_amdgcn_update_dpp(0, __builtin_bit_cast(int, v), 0x121, 0xf, 0xf, false)); }
; __device__ __forceinline__ float dpp_ror15(float v) { return __builtin_bit_cast(float, __builtin_amdgcn_update_dpp(0, __builtin_bit_cast(int, v), 0x12F, 0xf, 0xf, false)); }
;     template <bool BND> __device__ __forceinline__ void conv_gate(f32x4 (&acc)[2][2][4][2], const Unit& u, int wr, int wc, int fr, int fq, int tok0, int pcol) const {
;     ...
;                 for (int m = 0; m < 4; ++m) {
;                     const int r = ai * 128 + wr * 64 + m * 16 + fr, tok = tok0 + r;
;                     bool isfirst = false, islast = false;
;                     if (BND) { const int S1 = (tok < NPROMPT ? SEQP : SEQS) - 1, pos = tok & S1; isfirst = pos == 0; islast = pos == S1; }
;                     f32x4 cv[2];
; #pragma unroll
;                     for (int bj = 0; bj < 2; ++bj) {
;                         const f32x4 cur = acc[ai][bj][m][n];
;                         const f32x4 ups = m > 0 ? acc[ai][bj][m > 0 ? m - 1 : 0][n] : pe[bj];
;                         const f32x4 dns = m < 3 ? acc[ai][bj][m < 3 ? m + 1 : 3][n] : ne[bj];
;                         f32x4 prev, next;
; #pragma unroll
;                         for (int j = 0; j < 4; ++j) {
;                             const float t1 = fr == 15 ? ups[j] : cur[j]; float pv = dpp_ror1(t1);
;                             const float t2 = fr == 0 ? dns[j] : cur[j]; float nx = dpp_ror15(t2);
;                             if (BND) { prev[j] = isfirst ? 0.f : pv; next[j] = islast ? 0.f : nx; } else { prev[j] = pv; next[j] = nx; }
;                         }
;                         cv[bj] = w0[bj] * prev + w1[bj] * cur + w2[bj] * next + bb[bj];
;                     }
;                     f32x4 a;
; #pragma unroll
;                     for (int j = 0; j < 4; ++j) { const float g = cv[0][j]; const float sg = __builtin_amdgcn_rcpf(1.0f + __builtin_amdgcn_exp2f(-1.4426950408889634f * g)); a[j] = g * sg * cv[1][j]; }
;                     if (r >= 1 && r <= 254 && (!BND || tok < MTOK)) *(u32x2*)(act + (size_t)tok * DFF + fcol + 4 * n) = pack4(a);
;                     asm volatile("" ::: "memory");
.LBB0_756:
	s_or_b64 exec, exec, s[0:1]
	v_cndmask_b32_e64 v8, v184, v176, s[8:9]
	v_cndmask_b32_e64 v9, v184, v24, s[6:7]
	s_nop 0
	v_mov_b32_dpp v11, v8 row_ror:1 row_mask:0xf bank_mask:0xf
	v_cndmask_b32_e64 v10, v185, v25, s[6:7]
	v_mov_b32_dpp v8, v9 row_ror:15 row_mask:0xf bank_mask:0xf
	v_cndmask_b32_e64 v9, v185, v177, s[8:9]
	v_cndmask_b32_e64 v12, v182, v26, s[6:7]
	s_nop 0
	v_mov_b32_dpp v13, v9 row_ror:1 row_mask:0xf bank_mask:0xf
	v_cndmask_b32_e64 v16, v183, v27, s[6:7]
	v_cndmask_b32_e64 v17, v188, v180, s[8:9]
	v_mov_b32_dpp v9, v10 row_ror:15 row_mask:0xf bank_mask:0xf
	v_cndmask_b32_e64 v10, v182, v174, s[8:9]
	v_cndmask_b32_e64 v19, v189, v181, s[8:9]
	s_nop 0
	v_mov_b32_dpp v14, v10 row_ror:1 row_mask:0xf bank_mask:0xf
	v_cndmask_b32_e64 v21, v186, v178, s[8:9]
	v_mov_b32_dpp v10, v12 row_ror:15 row_mask:0xf bank_mask:0xf
	v_cndmask_b32_e64 v12, v183, v175, s[8:9]
	v_cndmask_b32_e64 v23, v187, v179, s[8:9]
	s_nop 0
	v_mov_b32_dpp v15, v12 row_ror:1 row_mask:0xf bank_mask:0xf
	v_cndmask_b32_e64 v64, v187, v31, s[6:7]
	s_nop 0
	v_mov_b32_dpp v12, v16 row_ror:15 row_mask:0xf bank_mask:0xf
	v_mov_b32_dpp v16, v17 row_ror:1 row_mask:0xf bank_mask:0xf
	v_cndmask_b32_e64 v17, v188, v28, s[6:7]
	s_nop 1
	v_mov_b32_dpp v18, v17 row_ror:15 row_mask:0xf bank_mask:0xf
	v_mov_b32_dpp v17, v19 row_ror:1 row_mask:0xf bank_mask:0xf
	v_cndmask_b32_e64 v19, v189, v29, s[6:7]
	s_nop 1
	v_mov_b32_dpp v20, v19 row_ror:15 row_mask:0xf bank_mask:0xf
	v_mov_b32_dpp v19, v21 row_ror:1 row_mask:0xf bank_mask:0xf
	v_cndmask_b32_e64 v21, v186, v30, s[6:7]
	s_nop 1
	v_mov_b32_dpp v22, v21 row_ror:15 row_mask:0xf bank_mask:0xf
	v_mov_b32_dpp v21, v23 row_ror:1 row_mask:0xf bank_mask:0xf
	v_mov_b32_dpp v23, v64 row_ror:15 row_mask:0xf bank_mask:0xf
	s_and_saveexec_b64 s[0:1], s[70:71]
	s_cbranch_execz .LBB0_758
	v_cndmask_b32_e64 v14, v14, 0, s[44:45]
	v_cndmask_b32_e64 v15, v15, 0, s[44:45]
	v_pk_mul_f32 v[14:15], v[42:43], v[14:15]
	v_cndmask_b32_e64 v65, v20, 0, s[34:35]
	v_cndmask_b32_e64 v20, v11, 0, s[44:45]
	v_pk_fma_f32 v[14:15], v[182:183], v[46:47], v[14:15]
	v_cndmask_b32_e64 v10, v10, 0, s[34:35]
	v_cndmask_b32_e64 v11, v12, 0, s[34:35]
	v_pk_fma_f32 v[10:11], v[38:39], v[10:11], v[14:15]
	v_cndmask_b32_e64 v64, v18, 0, s[34:35]
	v_pk_add_f32 v[10:11], v[34:35], v[10:11]
	v_cndmask_b32_e64 v18, v19, 0, s[44:45]
	v_mul_f32_e32 v12, 0xbfb8aa3b, v11
	v_exp_f32_e32 v12, v12
	v_cndmask_b32_e64 v19, v21, 0, s[44:45]
	v_cndmask_b32_e64 v21, v13, 0, s[44:45]
	v_mul_f32_e32 v13, 0xbfb8aa3b, v10
	v_add_f32_e32 v12, 1.0, v12
	v_pk_mul_f32 v[20:21], v[40:41], v[20:21]
	v_rcp_f32_e32 v12, v12
	v_exp_f32_e32 v13, v13
	v_pk_fma_f32 v[20:21], v[184:185], v[44:45], v[20:21]
	v_cndmask_b32_e64 v8, v8, 0, s[34:35]
	v_cndmask_b32_e64 v9, v9, 0, s[34:35]
	v_pk_fma_f32 v[8:9], v[36:37], v[8:9], v[20:21]
	v_mul_f32_e32 v11, v11, v12
	v_pk_add_f32 v[8:9], v[32:33], v[8:9]
	v_add_f32_e32 v12, 1.0, v13
	v_mul_f32_e32 v13, 0xbfb8aa3b, v9
	v_mul_f32_e32 v14, 0xbfb8aa3b, v8
	v_rcp_f32_e32 v12, v12
	v_exp_f32_e32 v13, v13
	v_exp_f32_e32 v14, v14
	v_cndmask_b32_e64 v16, v16, 0, s[44:45]
	v_mul_f32_e32 v10, v10, v12
	v_add_f32_e32 v12, 1.0, v13
	v_add_f32_e32 v13, 1.0, v14
	v_cndmask_b32_e64 v17, v17, 0, s[44:45]
	v_rcp_f32_e32 v12, v12
	v_rcp_f32_e32 v13, v13
	v_pk_mul_f32 v[18:19], v[62:63], v[18:19]
	v_pk_mul_f32 v[16:17], v[60:61], v[16:17]
	v_cndmask_b32_e64 v22, v22, 0, s[34:35]
	v_cndmask_b32_e64 v23, v23, 0, s[34:35]
	v_pk_fma_f32 v[16:17], v[188:189], v[56:57], v[16:17]
	v_pk_fma_f32 v[18:19], v[186:187], v[58:59], v[18:19]
	v_pk_fma_f32 v[16:17], v[52:53], v[64:65], v[16:17]
	v_pk_fma_f32 v[18:19], v[54:55], v[22:23], v[18:19]
	v_pk_add_f32 v[16:17], v[48:49], v[16:17]
	v_pk_add_f32 v[18:19], v[50:51], v[18:19]
	v_mul_f32_e32 v9, v9, v12
	v_mul_f32_e32 v8, v8, v13
	v_mul_f32_e32 v11, v11, v19
	v_mul_f32_e32 v10, v10, v18
	v_mul_f32_e32 v9, v9, v17
	v_mul_f32_e32 v8, v8, v16
	v_cvt_pk_bf16_f32 v8, v8, v9
	v_cvt_pk_bf16_f32 v9, v10, v11
	v_mov_b64_e32 v[10:11], s[88:89]
	s_movk_i32 s4, 0x1600
	v_mad_i64_i32 v[10:11], s[4:5], v98, s4, v[10:11]
	v_lshl_add_u64 v[10:11], v[190:191], 1, v[10:11]
	global_store_dwordx2 v[10:11], v[8:9], off offset:8
; __device__ __forceinline__ u32x2 pack4(f32x4 a) { u32x2 w; w.x = cvt_pk_bf16(a[0], a[1]); w.y = cvt_pk_bf16(a[2], a[3]); return w; }
; __device__ __forceinline__ float dpp_ror1(float v) { return __builtin_bit_cast(float, __builtin_amdgcn_update_dpp(0, __builtin_bit_cast(int, v), 0x121, 0xf, 0xf, false)); }
; __device__ __forceinline__ float dpp_ror15(float v) { return __builtin_bit_cast(float, __builtin_amdgcn_update_dpp(0, __builtin_bit_cast(int, v), 0x12F, 0xf, 0xf, false)); }
;     template <bool BND> __device__ __forceinline__ void conv_gate(f32x4 (&acc)[2][2][4][2], const Unit& u, int wr, int wc, int fr, int fq, int tok0, int pcol) const {
;     ...
;                 for (int m = 0; m < 4; ++m) {
;                     const int r = ai * 128 + wr * 64 + m * 16 + fr, tok = tok0 + r;
;                     bool isfirst = false, islast = false;
;                     if (BND) { const int S1 = (tok < NPROMPT ? SEQP : SEQS) - 1, pos = tok & S1; isfirst = pos == 0; islast = pos == S1; }
;                     f32x4 cv[2];
; #pragma unroll
;                     for (int bj = 0; bj < 2; ++bj) {
;                         const f32x4 cur = acc[ai][bj][m][n];
;                         const f32x4 ups = m > 0 ? acc[ai][bj][m > 0 ? m - 1 : 0][n] : pe[bj];
;                         const f32x4 dns = m < 3 ? acc[ai][bj][m < 3 ? m + 1 : 3][n] : ne[bj];
;                         f32x4 prev, next;
; #pragma unroll
;                         for (int j = 0; j < 4; ++j) {
;                             const float t1 = fr == 15 ? ups[j] : cur[j]; float pv = dpp_ror1(t1);
;                             const float t2 = fr == 0 ? dns[j] : cur[j]; float nx = dpp_ror15(t2);
;                             if (BND) { prev[j] = isfirst ? 0.f : pv; next[j] = islast ? 0.f : nx; } else { prev[j] = pv; next[j] = nx; }
;                         }
;                         cv[bj] = w0[bj] * prev + w1[bj] * cur + w2[bj] * next + bb[bj];
;                     }
;                     f32x4 a;
; #pragma unroll
;                     for (int j = 0; j < 4; ++j) { const float g = cv[0][j]; const float sg = __builtin_amdgcn_rcpf(1.0f + __builtin_amdgcn_exp2f(-1.4426950408889634f * g)); a[j] = g * sg * cv[1][j]; }
;                     if (r >= 1 && r <= 254 && (!BND || tok < MTOK)) *(u32x2*)(act + (size_t)tok * DFF + fcol + 4 * n) = pack4(a);
;                     asm volatile("" ::: "memory");
.LBB0_758:
	s_or_b64 exec, exec, s[0:1]
	v_cndmask_b32_e64 v9, v24, v184, s[8:9]
	v_cndmask_b32_e64 v10, v25, v185, s[8:9]
	v_cndmask_b32_e64 v11, v26, v182, s[8:9]
	v_mov_b32_dpp v8, v9 row_ror:1 row_mask:0xf bank_mask:0xf
	v_cndmask_b32_e64 v9, v24, v0, s[6:7]
	v_cndmask_b32_e64 v12, v27, v183, s[8:9]
	v_cndmask_b32_e64 v13, v28, v188, s[8:9]
	v_mov_b32_dpp v0, v9 row_ror:15 row_mask:0xf bank_mask:0xf
	v_cndmask_b32_e64 v14, v29, v189, s[8:9]
	v_cndmask_b32_e64 v15, v30, v186, s[8:9]
	v_mov_b32_dpp v9, v10 row_ror:1 row_mask:0xf bank_mask:0xf
	v_cndmask_b32_e64 v10, v25, v1, s[6:7]
	v_cndmask_b32_e64 v16, v31, v187, s[8:9]
	s_nop 0
	v_mov_b32_dpp v1, v10 row_ror:15 row_mask:0xf bank_mask:0xf
	v_mov_b32_dpp v10, v11 row_ror:1 row_mask:0xf bank_mask:0xf
	v_cndmask_b32_e64 v11, v26, v2, s[6:7]
	s_nop 1
	v_mov_b32_dpp v2, v11 row_ror:15 row_mask:0xf bank_mask:0xf
	v_mov_b32_dpp v11, v12 row_ror:1 row_mask:0xf bank_mask:0xf
	v_cndmask_b32_e64 v12, v27, v3, s[6:7]
	s_nop 1
	v_mov_b32_dpp v3, v12 row_ror:15 row_mask:0xf bank_mask:0xf
	v_mov_b32_dpp v12, v13 row_ror:1 row_mask:0xf bank_mask:0xf
	v_cndmask_b32_e64 v13, v28, v4, s[6:7]
	s_nop 1
	v_mov_b32_dpp v4, v13 row_ror:15 row_mask:0xf bank_mask:0xf
	v_mov_b32_dpp v13, v14 row_ror:1 row_mask:0xf bank_mask:0xf
	v_cndmask_b32_e64 v14, v29, v5, s[6:7]
	s_nop 1
	v_mov_b32_dpp v5, v14 row_ror:15 row_mask:0xf bank_mask:0xf
	v_mov_b32_dpp v14, v15 row_ror:1 row_mask:0xf bank_mask:0xf
	v_cndmask_b32_e64 v15, v30, v6, s[6:7]
	s_nop 1
	v_mov_b32_dpp v6, v15 row_ror:15 row_mask:0xf bank_mask:0xf
	v_mov_b32_dpp v15, v16 row_ror:1 row_mask:0xf bank_mask:0xf
	v_cndmask_b32_e64 v16, v31, v7, s[6:7]
	s_nop 1
	v_mov_b32_dpp v7, v16 row_ror:15 row_mask:0xf bank_mask:0xf
	s_and_saveexec_b64 s[0:1], s[54:55]
	s_cbranch_execz .LBB0_760
	v_cndmask_b32_e64 v10, v10, 0, s[46:47]
	v_cndmask_b32_e64 v11, v11, 0, s[46:47]
	v_pk_mul_f32 v[10:11], v[42:43], v[10:11]
	v_cndmask_b32_e64 v2, v2, 0, s[36:37]
	v_pk_fma_f32 v[10:11], v[26:27], v[46:47], v[10:11]
	v_cndmask_b32_e64 v3, v3, 0, s[36:37]
	v_pk_fma_f32 v[2:3], v[38:39], v[2:3], v[10:11]
	v_cndmask_b32_e64 v8, v8, 0, s[46:47]
	v_pk_add_f32 v[2:3], v[34:35], v[2:3]
	v_cndmask_b32_e64 v9, v9, 0, s[46:47]
	v_mul_f32_e32 v10, 0xbfb8aa3b, v3
	v_exp_f32_e32 v10, v10
	v_pk_mul_f32 v[8:9], v[40:41], v[8:9]
	v_cndmask_b32_e64 v0, v0, 0, s[36:37]
	v_pk_fma_f32 v[8:9], v[24:25], v[44:45], v[8:9]
	v_cndmask_b32_e64 v1, v1, 0, s[36:37]
	v_pk_fma_f32 v[0:1], v[36:37], v[0:1], v[8:9]
	v_add_f32_e32 v8, 1.0, v10
	v_cndmask_b32_e64 v14, v14, 0, s[46:47]
	v_cndmask_b32_e64 v15, v15, 0, s[46:47]
	v_rcp_f32_e32 v8, v8
	v_mul_f32_e32 v9, 0xbfb8aa3b, v2
	v_pk_mul_f32 v[14:15], v[62:63], v[14:15]
	v_exp_f32_e32 v9, v9
	v_pk_fma_f32 v[14:15], v[30:31], v[58:59], v[14:15]
	v_cndmask_b32_e64 v6, v6, 0, s[36:37]
	v_cndmask_b32_e64 v7, v7, 0, s[36:37]
	v_pk_fma_f32 v[6:7], v[54:55], v[6:7], v[14:15]
	v_pk_add_f32 v[0:1], v[32:33], v[0:1]
	v_pk_add_f32 v[6:7], v[50:51], v[6:7]
	v_mul_f32_e32 v3, v3, v8
	v_mul_f32_e32 v3, v3, v7
	v_add_f32_e32 v7, 1.0, v9
	v_mul_f32_e32 v8, 0xbfb8aa3b, v1
	v_mul_f32_e32 v9, 0xbfb8aa3b, v0
	v_rcp_f32_e32 v7, v7
	v_exp_f32_e32 v8, v8
	v_exp_f32_e32 v9, v9
	v_cndmask_b32_e64 v12, v12, 0, s[46:47]
	v_mul_f32_e32 v2, v2, v7
	v_add_f32_e32 v7, 1.0, v8
	v_add_f32_e32 v8, 1.0, v9
	v_cndmask_b32_e64 v13, v13, 0, s[46:47]
	v_rcp_f32_e32 v7, v7
	v_rcp_f32_e32 v8, v8
	v_pk_mul_f32 v[12:13], v[60:61], v[12:13]
	v_cndmask_b32_e64 v4, v4, 0, s[36:37]
	v_pk_fma_f32 v[12:13], v[28:29], v[56:57], v[12:13]
	v_cndmask_b32_e64 v5, v5, 0, s[36:37]
	v_pk_fma_f32 v[4:5], v[52:53], v[4:5], v[12:13]
	v_mul_f32_e32 v1, v1, v7
	v_pk_add_f32 v[4:5], v[48:49], v[4:5]
	v_mul_f32_e32 v0, v0, v8
	v_mul_f32_e32 v2, v2, v6
	v_mul_f32_e32 v1, v1, v5
	v_mul_f32_e32 v0, v0, v4
	v_cvt_pk_bf16_f32 v0, v0, v1
	v_cvt_pk_bf16_f32 v1, v2, v3
	v_mov_b64_e32 v[2:3], s[88:89]
	s_movk_i32 s4, 0x1600
	v_mad_i64_i32 v[2:3], s[4:5], v99, s4, v[2:3]
	v_lshl_add_u64 v[2:3], v[190:191], 1, v[2:3]
	global_store_dwordx2 v[2:3], v[0:1], off offset:8
